# dense unit prologue de-waterfall: both rope/gain table load batches issued with the q rows and ring DMA before the first wait (one latency instead of three), counted waits
# baseline (speedup 1.0000x reference)
; __device__ __forceinline__ int v_rd_base(int lane) { return ((lane & 3) << 3) | (((lane >> 2) & 3) << 6) | (((lane >> 4) & 1) << 5) | (((lane >> 5) & 1) << 8); }
;     ...
;   const bf16* Qw = Qb + (long)(wid * QBLK + r32) * qs + hi * 8;
; #pragma unroll
;   for (int d0 = 0; d0 < 8; ++d0) qr[d0] = St::ld8(Qw + d0 * 16);
;   const int vb0 = (int)(uintptr_t)V_lds + v_rd_base(lane);
;   const int kb = DIL ? i0 - 64 : 0;
;     ...
;   int krow[2], kcol[2], vrow[2], vcol[2];
; #pragma unroll
;   for (int i = 0; i < 2; ++i) { const int pc = 2 * wid + i;
;     krow[i] = pc * 4 + (lane >> 4); kcol[i] = (((lane & 15) ^ (krow[i] & 7)) << 3);
;     const int sub = pc * 2 + (lane >> 5), kk = ((sub >> 2) << 3) + ((lane & 31) >> 2);
;     vrow[i] = kk; vcol[i] = ((sub & 3) << 5) + ((lane & 3) << 3); }
;   unsigned kdo[2], vdo[2];
; #pragma unroll
;   for (int i = 0; i < 2; ++i) { kdo[i] = (unsigned)(krow[i] * (int)ks + kcol[i]); vdo[i] = (unsigned)(vrow[i] * (int)ks + vcol[i]); }
;     ...
;   f32x16 pA0, pA1, pB0, pB1; float mnA, mnB, alA, alB; bf16x8 pa0, pa1, pa2, pa3; const int NT = DIL ? 6 : seq / KVBLK;
;   DMA(0, 0); DMA(1, 1);
;   if constexpr (!DIL && MK_PP) { DMA(2, 2); asm volatile("s_waitcnt vmcnt(8)\n\ts_barrier" ::: "memory"); }
;   else asm volatile("s_waitcnt vmcnt(4)\n\ts_barrier" ::: "memory");
;     ...
;     const int tpos = tq0 + wid * QBLK + r32, grow = tpos >> 6, gcol = tpos & 63;
; #pragma unroll
;     for (int hf = 0; hf < 2; ++hf) {
;       const int trow = hf ? 128 + gcol : grow;
; #pragma unroll
;       for (int dd = 0; dd < 2; ++dd) { const int d0 = hf * 4 + dd, f0 = dd * 16 + hi * 8;
;         const f32x8 cs = *(const f32x8*)(rcos + trow * 32 + f0), sn = *(const f32x8*)(rsin + trow * 32 + f0);
;         const f32x8 g1 = *(const f32x8*)(qgain + d0 * 16 + hi * 8), g2 = *(const f32x8*)(qgain + (d0 + 2) * 16 + hi * 8);
.LBB0_49:
	s_ashr_i32 s2, s25, 8
	s_bfe_u32 s10, s25, 0x10007
	s_lshl_b32 s0, s10, 2
	s_bfe_u32 s1, s25, 0x20005
	s_ashr_i32 s3, s2, 31
	s_or_b32 s11, s0, s1
	s_lshl_b64 s[40:41], s[2:3], 21
	s_add_u32 s12, s34, s40
	s_addc_u32 s13, s35, s41
	s_lshl_b32 s0, s25, 8
	s_and_b32 s51, s0, 0x1f00
	s_lshl_b32 s0, s51, 8
	s_lshl_b32 s1, s11, 22
	s_or_b32 s0, s1, s0
	s_add_u32 s0, s12, s0
	s_addc_u32 s1, s13, 0
	s_lshl_b32 s10, s10, 22
	s_add_u32 s44, s12, s10
	s_addc_u32 s45, s13, 0
	s_add_u32 s38, s44, 0x2000000
	s_addc_u32 s39, s45, 0
	v_mov_b32_e32 v212, v214
	s_add_u32 s42, s44, 0x2800000
	s_addc_u32 s43, s45, 0
	v_readfirstlane_b32 s12, v212
	s_ashr_i32 s10, s12, 6
	v_and_b32_e32 v232, 31, v212
	s_lshl_b32 s50, s10, 5
	v_or_b32_e32 v2, s50, v232
	v_ashrrev_i32_e32 v3, 31, v2
	v_bfe_u32 v233, v212, 5, 1
	v_lshlrev_b64 v[4:5], 8, v[2:3]
	v_lshl_add_u64 v[4:5], s[0:1], 0, v[4:5]
	v_lshlrev_b32_e32 v0, 4, v233
	v_lshl_add_u64 v[4:5], v[4:5], 0, v[0:1]
	global_load_dwordx4 v[130:133], v[4:5], off
	global_load_dwordx4 v[138:141], v[4:5], off offset:32
	global_load_dwordx4 v[134:137], v[4:5], off offset:64
	global_load_dwordx4 v[142:145], v[4:5], off offset:96
	global_load_dwordx4 v[146:149], v[4:5], off offset:128
	global_load_dwordx4 v[154:157], v[4:5], off offset:160
	global_load_dwordx4 v[150:153], v[4:5], off offset:192
	global_load_dwordx4 v[158:161], v[4:5], off offset:224
	s_lshl_b32 s0, s10, 3
	v_bfe_u32 v230, v212, 4, 2
	v_and_b32_e32 v231, 15, v212
	v_lshlrev_b32_e32 v3, 3, v212
	v_or3_b32 v5, s0, v230, 4
	v_and_b32_e32 v242, 24, v3
	v_bitop3_b32 v3, v230, v212, 15 bitop3:0x78
	v_bitop3_b32 v4, v5, v231, 7 bitop3:0x6c
	v_lshlrev_b32_e32 v241, 3, v3
	v_and_b32_e32 v162, 32, v212
	v_lshlrev_b32_e32 v213, 3, v4
	s_lshl_b32 s15, s10, 10
	v_lshlrev_b32_e32 v240, 7, v230
	v_lshlrev_b32_e32 v6, 5, v212
	v_or_b32_e32 v3, v242, v162
	v_or3_b32 v4, v241, v240, s15
	v_and_b32_e32 v243, 0x380, v6
	v_lshl_or_b32 v8, v5, 7, v213
	s_lshl_b32 s82, s10, 11
	v_mov_b32_e32 v5, v1
	v_or3_b32 v6, v243, v3, s15
	v_lshlrev_b64 v[4:5], 1, v[4:5]
	s_add_i32 s13, s82, 0
	v_mov_b32_e32 v7, v1
	v_or_b32_e32 v10, 64, v6
	v_lshl_add_u64 v[12:13], s[38:39], 0, v[4:5]
	s_mov_b32 m0, s13
	v_lshlrev_b64 v[6:7], 1, v[6:7]
	s_add_i32 s14, s88, s82
	v_mov_b32_e32 v9, v1
	global_load_lds_dwordx4 v[12:13], off
	v_lshl_add_u64 v[12:13], s[42:43], 0, v[6:7]
	s_mov_b32 m0, s14
	v_lshlrev_b64 v[8:9], 1, v[8:9]
	global_load_lds_dwordx4 v[12:13], off
	v_lshl_add_u64 v[12:13], s[38:39], 0, v[8:9]
	s_or_b32 s83, s82, 0x400
	s_add_i32 m0, s13, 0x400
	v_mov_b32_e32 v11, v1
	global_load_lds_dwordx4 v[12:13], off
	s_add_i32 m0, s88, s83
	s_add_u32 s0, s44, 0x2004000
	v_lshlrev_b64 v[10:11], 1, v[10:11]
	s_addc_u32 s1, s45, 0
	v_lshl_add_u64 v[12:13], s[42:43], 0, v[10:11]
	s_add_u32 s38, s44, 0x2804000
	global_load_lds_dwordx4 v[12:13], off
	s_addc_u32 s39, s45, 0
	v_lshl_add_u64 v[12:13], s[0:1], 0, v[4:5]
	s_add_i32 m0, s13, 0x4000
	v_lshlrev_b32_e32 v2, 7, v2
	global_load_lds_dwordx4 v[12:13], off
	v_lshl_add_u64 v[12:13], s[38:39], 0, v[6:7]
	s_add_i32 m0, s89, s82
	v_and_b32_e32 v2, 0x1f80, v2
	global_load_lds_dwordx4 v[12:13], off
	v_lshl_add_u64 v[12:13], s[0:1], 0, v[8:9]
	s_add_i32 m0, s13, 0x4400
	v_or_b32_e32 v2, 0x4000, v2
	global_load_lds_dwordx4 v[12:13], off
	s_add_i32 m0, s89, s83
	s_add_u32 s0, s44, 0x2008000
	s_addc_u32 s1, s45, 0
	v_lshl_add_u64 v[12:13], s[38:39], 0, v[10:11]
	s_add_u32 s38, s44, 0x2808000
	global_load_lds_dwordx4 v[12:13], off
	s_addc_u32 s39, s45, 0
	v_lshl_add_u64 v[4:5], s[0:1], 0, v[4:5]
	s_add_i32 m0, s13, 0x8000
	v_mov_b32_e32 v3, v1
	global_load_lds_dwordx4 v[4:5], off
	v_lshl_add_u64 v[4:5], s[38:39], 0, v[6:7]
	s_add_i32 m0, s90, s82
	v_mov_b32_e32 v163, v1
	global_load_lds_dwordx4 v[4:5], off
	v_lshl_add_u64 v[4:5], s[0:1], 0, v[8:9]
	s_add_i32 m0, s13, 0x8400
	s_nop 0
	global_load_lds_dwordx4 v[4:5], off
	v_lshl_add_u64 v[4:5], s[38:39], 0, v[10:11]
	s_add_i32 m0, s90, s83
	s_nop 0
	global_load_lds_dwordx4 v[4:5], off
	v_lshl_add_u64 v[4:5], s[36:37], 0, v[2:3]
	v_lshl_add_u64 v[2:3], s[46:47], 0, v[2:3]
	v_lshl_add_u64 v[42:43], v[4:5], 0, v[162:163]
	v_lshl_add_u64 v[46:47], v[2:3], 0, v[162:163]
	global_load_dwordx4 v[10:13], v162, s[18:19] offset:336
	global_load_dwordx4 v[14:17], v162, s[18:19] offset:464
	global_load_dwordx4 v[6:9], v[46:47], off offset:80
	global_load_dwordx4 v[2:5], v[42:43], off offset:80
	global_load_dwordx4 v[30:33], v162, s[18:19] offset:320
	global_load_dwordx4 v[26:29], v162, s[18:19] offset:448
	global_load_dwordx4 v[22:25], v[46:47], off offset:64
	global_load_dwordx4 v[18:21], v[42:43], off offset:64
	global_load_dwordx4 v[34:37], v162, s[18:19] offset:272
	global_load_dwordx4 v[50:53], v162, s[18:19] offset:256
	global_load_dwordx4 v[38:41], v162, s[18:19] offset:400
	global_load_dwordx4 v[54:57], v162, s[18:19] offset:384
	v_or_b32_e32 v44, s51, v232
	v_add_u32_e32 v44, s50, v44
	v_ashrrev_i32_e32 v44, 1, v44
	v_and_b32_e32 v44, 0xffffffe0, v44
	v_ashrrev_i32_e32 v45, 31, v44
	v_lshlrev_b64 v[44:45], 2, v[44:45]
	v_lshl_add_u64 v[48:49], s[36:37], 0, v[44:45]
	v_lshl_add_u64 v[48:49], v[48:49], 0, v[162:163]
	global_load_dwordx4 v[114:117], v[48:49], off
	global_load_dwordx4 v[98:101], v[48:49], off offset:16
	v_lshl_add_u64 v[44:45], s[46:47], 0, v[44:45]
	v_lshl_add_u64 v[44:45], v[44:45], 0, v[162:163]
	global_load_dwordx4 v[118:121], v[44:45], off
	global_load_dwordx4 v[102:105], v[44:45], off offset:16
	global_load_dwordx4 v[126:129], v162, s[18:19]
	global_load_dwordx4 v[110:113], v162, s[18:19] offset:16
	global_load_dwordx4 v[122:125], v162, s[18:19] offset:128
	global_load_dwordx4 v[106:109], v162, s[18:19] offset:144
	global_load_dwordx4 v[82:85], v[48:49], off offset:64
	global_load_dwordx4 v[66:69], v[48:49], off offset:80
	global_load_dwordx4 v[86:89], v[44:45], off offset:64
	global_load_dwordx4 v[70:73], v[44:45], off offset:80
	global_load_dwordx4 v[90:93], v162, s[18:19] offset:64
	global_load_dwordx4 v[74:77], v162, s[18:19] offset:80
	global_load_dwordx4 v[94:97], v162, s[18:19] offset:192
	global_load_dwordx4 v[78:81], v162, s[18:19] offset:208
	global_load_dwordx4 v[58:61], v[42:43], off
	s_nop 0
	global_load_dwordx4 v[42:45], v[42:43], off offset:16
	s_nop 0
	global_load_dwordx4 v[62:65], v[46:47], off
	s_nop 0
	global_load_dwordx4 v[46:49], v[46:47], off offset:16
	s_waitcnt vmcnt(44)
	v_and_b32_e32 v237, 0xffff0000, v134
	v_and_b32_e32 v236, 0xffff0000, v130
	s_waitcnt vmcnt(40)
	s_barrier
;     ...
;     float x[8][8]; float ss = 0.f;
; #pragma unroll
;     for (int d0 = 0; d0 < 8; ++d0)
; #pragma unroll
;       for (int i = 0; i < 8; ++i) { x[d0][i] = __uint_as_float(((unsigned)(unsigned short)qr[d0][i]) << 16); ss += x[d0][i] * x[d0][i]; }
;     { auto rr = __builtin_amdgcn_permlane32_swap(__float_as_uint(ss), __float_as_uint(ss), false, false); ss = __uint_as_float(rr[0]) + __uint_as_float(rr[1]); }
	v_lshlrev_b32_e32 v165, 16, v161
	v_and_b32_e32 v167, 0xffff0000, v161
	v_lshlrev_b32_e32 v161, 16, v159
	v_and_b32_e32 v179, 0xffff0000, v159
	v_lshlrev_b32_e32 v159, 16, v153
	v_and_b32_e32 v187, 0xffff0000, v153
	v_lshlrev_b32_e32 v153, 16, v151
	v_and_b32_e32 v191, 0xffff0000, v151
	v_lshlrev_b32_e32 v151, 16, v145
	v_and_b32_e32 v195, 0xffff0000, v145
	v_lshlrev_b32_e32 v145, 16, v143
	v_and_b32_e32 v199, 0xffff0000, v143
	v_lshlrev_b32_e32 v143, 16, v137
	v_and_b32_e32 v205, 0xffff0000, v137
	v_lshlrev_b32_e32 v203, 16, v136
	v_lshlrev_b32_e32 v202, 16, v132
	v_and_b32_e32 v211, 0xffff0000, v136
	v_and_b32_e32 v210, 0xffff0000, v132
	v_lshlrev_b32_e32 v132, 16, v131
	v_and_b32_e32 v234, 0xffff0000, v131
	v_lshlrev_b32_e32 v137, 16, v134
	v_lshlrev_b32_e32 v136, 16, v130
	v_pk_mul_f32 v[130:131], v[236:237], v[236:237]
	v_lshlrev_b32_e32 v164, 16, v157
	v_and_b32_e32 v166, 0xffff0000, v157
	v_lshlrev_b32_e32 v173, 16, v160
	v_and_b32_e32 v157, 0xffff0000, v160
	v_lshlrev_b32_e32 v160, 16, v155
	v_and_b32_e32 v178, 0xffff0000, v155
	v_lshlrev_b32_e32 v185, 16, v158
	v_and_b32_e32 v155, 0xffff0000, v158
	v_lshlrev_b32_e32 v158, 16, v149
	v_and_b32_e32 v186, 0xffff0000, v149
	v_lshlrev_b32_e32 v189, 16, v152
	v_and_b32_e32 v149, 0xffff0000, v152
	v_lshlrev_b32_e32 v152, 16, v147
	v_and_b32_e32 v190, 0xffff0000, v147
	v_lshlrev_b32_e32 v193, 16, v150
	v_and_b32_e32 v147, 0xffff0000, v150
	v_lshlrev_b32_e32 v150, 16, v141
	v_and_b32_e32 v194, 0xffff0000, v141
	v_lshlrev_b32_e32 v197, 16, v144
	v_and_b32_e32 v141, 0xffff0000, v144
	v_lshlrev_b32_e32 v144, 16, v139
	v_and_b32_e32 v198, 0xffff0000, v139
	v_lshlrev_b32_e32 v201, 16, v142
	v_and_b32_e32 v139, 0xffff0000, v142
	v_lshlrev_b32_e32 v142, 16, v133
	v_and_b32_e32 v204, 0xffff0000, v133
	v_lshlrev_b32_e32 v133, 16, v135
	v_and_b32_e32 v235, 0xffff0000, v135
	v_pk_fma_f32 v[134:135], v[136:137], v[136:137], v[130:131]
	v_lshlrev_b32_e32 v200, 16, v138
	v_pk_fma_f32 v[134:135], v[132:133], v[132:133], v[134:135]
	v_and_b32_e32 v138, 0xffff0000, v138
	v_pk_fma_f32 v[134:135], v[234:235], v[234:235], v[134:135]
	v_pk_fma_f32 v[134:135], v[202:203], v[202:203], v[134:135]
	v_pk_fma_f32 v[134:135], v[210:211], v[210:211], v[134:135]
	v_lshlrev_b32_e32 v196, 16, v140
	v_pk_fma_f32 v[134:135], v[142:143], v[142:143], v[134:135]
	v_pk_fma_f32 v[134:135], v[204:205], v[204:205], v[134:135]
	v_and_b32_e32 v140, 0xffff0000, v140
	v_pk_fma_f32 v[134:135], v[200:201], v[200:201], v[134:135]
	v_pk_fma_f32 v[134:135], v[138:139], v[138:139], v[134:135]
	v_pk_fma_f32 v[134:135], v[144:145], v[144:145], v[134:135]
	v_pk_fma_f32 v[134:135], v[198:199], v[198:199], v[134:135]
	s_waitcnt vmcnt(20)
	v_mov_b32_e32 v176, v10
	v_pk_fma_f32 v[134:135], v[196:197], v[196:197], v[134:135]
	v_mul_f32_e32 v10, v137, v137
	v_pk_fma_f32 v[134:135], v[140:141], v[140:141], v[134:135]
	v_pk_fma_f32 v[134:135], v[150:151], v[150:151], v[134:135]
	v_pk_fma_f32 v[134:135], v[194:195], v[194:195], v[134:135]
	v_pk_add_f32 v[134:135], v[10:11], v[134:135] op_sel_hi:[0,1]
	v_pk_add_f32 v[130:131], v[130:131], v[134:135] op_sel:[1,0] op_sel_hi:[0,1]
	v_mul_f32_e32 v10, v133, v133
	v_pk_add_f32 v[130:131], v[10:11], v[130:131] op_sel_hi:[0,1]
	v_mul_f32_e32 v10, v235, v235
	v_pk_add_f32 v[130:131], v[10:11], v[130:131] op_sel_hi:[0,1]
	v_mul_f32_e32 v10, v203, v203
	v_pk_add_f32 v[130:131], v[10:11], v[130:131] op_sel_hi:[0,1]
	v_mul_f32_e32 v10, v211, v211
	v_pk_add_f32 v[130:131], v[10:11], v[130:131] op_sel_hi:[0,1]
	v_mul_f32_e32 v10, v143, v143
	v_pk_add_f32 v[130:131], v[10:11], v[130:131] op_sel_hi:[0,1]
	v_mul_f32_e32 v10, v205, v205
	v_pk_add_f32 v[130:131], v[10:11], v[130:131] op_sel_hi:[0,1]
	v_mul_f32_e32 v10, v201, v201
	v_pk_add_f32 v[130:131], v[10:11], v[130:131] op_sel_hi:[0,1]
	v_mul_f32_e32 v10, v139, v139
	v_pk_add_f32 v[130:131], v[10:11], v[130:131] op_sel_hi:[0,1]
	v_mul_f32_e32 v10, v145, v145
	v_pk_add_f32 v[130:131], v[10:11], v[130:131] op_sel_hi:[0,1]
	v_mul_f32_e32 v10, v199, v199
	v_pk_add_f32 v[130:131], v[10:11], v[130:131] op_sel_hi:[0,1]
	v_mul_f32_e32 v10, v197, v197
	v_pk_add_f32 v[130:131], v[10:11], v[130:131] op_sel_hi:[0,1]
	v_mul_f32_e32 v10, v141, v141
	s_nop 0
	s_nop 0
	s_nop 0
	v_pk_add_f32 v[130:131], v[10:11], v[130:131] op_sel_hi:[0,1]
	v_mul_f32_e32 v10, v151, v151
	v_pk_add_f32 v[130:131], v[10:11], v[130:131] op_sel_hi:[0,1]
	v_mul_f32_e32 v10, v195, v195
	v_lshlrev_b32_e32 v192, 16, v146
	v_pk_add_f32 v[130:131], v[10:11], v[130:131] op_sel_hi:[0,1]
	v_and_b32_e32 v146, 0xffff0000, v146
	v_pk_fma_f32 v[130:131], v[192:193], v[192:193], v[130:131]
	v_lshlrev_b32_e32 v188, 16, v148
	v_pk_fma_f32 v[130:131], v[146:147], v[146:147], v[130:131]
	v_and_b32_e32 v148, 0xffff0000, v148
	v_pk_fma_f32 v[130:131], v[152:153], v[152:153], v[130:131]
	v_lshlrev_b32_e32 v184, 16, v154
	v_pk_fma_f32 v[130:131], v[190:191], v[190:191], v[130:131]
	v_and_b32_e32 v154, 0xffff0000, v154
	v_pk_fma_f32 v[130:131], v[188:189], v[188:189], v[130:131]
	v_lshlrev_b32_e32 v172, 16, v156
	v_pk_fma_f32 v[130:131], v[148:149], v[148:149], v[130:131]
	v_and_b32_e32 v156, 0xffff0000, v156
	v_pk_fma_f32 v[130:131], v[158:159], v[158:159], v[130:131]
	v_mul_f32_e32 v10, v193, v193
	v_pk_fma_f32 v[130:131], v[186:187], v[186:187], v[130:131]
	v_mov_b32_e32 v208, v167
	v_pk_fma_f32 v[130:131], v[184:185], v[184:185], v[130:131]
	v_mov_b32_e32 v209, v165
	v_pk_fma_f32 v[130:131], v[154:155], v[154:155], v[130:131]
	v_mov_b32_e32 v170, v12
	v_pk_fma_f32 v[130:131], v[160:161], v[160:161], v[130:131]
	v_mov_b32_e32 v177, v14
	v_pk_fma_f32 v[130:131], v[178:179], v[178:179], v[130:131]
	v_mov_b32_e32 v171, v16
;     ...
;     { auto rr = __builtin_amdgcn_permlane32_swap(__float_as_uint(ss), __float_as_uint(ss), false, false); ss = __uint_as_float(rr[0]) + __uint_as_float(rr[1]); }
;     const float rstd = 1.0f / sqrtf(ss * (1.0f / 128.f) + 1e-6f), qsc = MK_NEGM ? SCALE * LOG2E : 1.0f;
;     const int tpos = tq0 + wid * QBLK + r32, grow = tpos >> 6, gcol = tpos & 63;
; #pragma unroll
;     for (int hf = 0; hf < 2; ++hf) {
;       const int trow = hf ? 128 + gcol : grow;
; #pragma unroll
;       for (int dd = 0; dd < 2; ++dd) { const int d0 = hf * 4 + dd, f0 = dd * 16 + hi * 8;
;         const f32x8 cs = *(const f32x8*)(rcos + trow * 32 + f0), sn = *(const f32x8*)(rsin + trow * 32 + f0);
;         const f32x8 g1 = *(const f32x8*)(qgain + d0 * 16 + hi * 8), g2 = *(const f32x8*)(qgain + (d0 + 2) * 16 + hi * 8);
; #pragma unroll
;         for (int i = 0; i < 8; ++i) { const float y1 = x[d0][i] * rstd * g1[i], y2 = x[d0 + 2][i] * rstd * g2[i];
;           x[d0][i] = (y1 * cs[i] - y2 * sn[i]) * qsc; x[d0 + 2][i] = (y1 * sn[i] + y2 * cs[i]) * qsc; } } }
	v_pk_fma_f32 v[130:131], v[172:173], v[172:173], v[130:131]
	v_mov_b32_e32 v183, v28
	v_pk_fma_f32 v[130:131], v[156:157], v[156:157], v[130:131]
	v_mov_b32_e32 v182, v32
	v_pk_fma_f32 v[130:131], v[164:165], v[164:165], v[130:131]
	v_mov_b32_e32 v180, v24
	v_pk_fma_f32 v[130:131], v[166:167], v[166:167], v[130:131]
	v_mov_b32_e32 v181, v20
	v_pk_add_f32 v[130:131], v[10:11], v[130:131] op_sel_hi:[0,1]
	v_mul_f32_e32 v10, v147, v147
	v_pk_add_f32 v[130:131], v[10:11], v[130:131] op_sel_hi:[0,1]
	v_mul_f32_e32 v10, v153, v153
	v_pk_add_f32 v[130:131], v[10:11], v[130:131] op_sel_hi:[0,1]
	v_mul_f32_e32 v10, v191, v191
	v_pk_add_f32 v[130:131], v[10:11], v[130:131] op_sel_hi:[0,1]
	v_mul_f32_e32 v10, v189, v189
	v_pk_add_f32 v[130:131], v[10:11], v[130:131] op_sel_hi:[0,1]
	v_mul_f32_e32 v10, v149, v149
	v_pk_add_f32 v[130:131], v[10:11], v[130:131] op_sel_hi:[0,1]
	v_mul_f32_e32 v10, v159, v159
	v_pk_add_f32 v[130:131], v[10:11], v[130:131] op_sel_hi:[0,1]
	v_mul_f32_e32 v10, v187, v187
	v_pk_add_f32 v[130:131], v[10:11], v[130:131] op_sel_hi:[0,1]
	v_mul_f32_e32 v10, v185, v185
	v_pk_add_f32 v[130:131], v[10:11], v[130:131] op_sel_hi:[0,1]
	v_mul_f32_e32 v10, v155, v155
	v_pk_add_f32 v[130:131], v[10:11], v[130:131] op_sel_hi:[0,1]
	v_mul_f32_e32 v10, v161, v161
	v_pk_add_f32 v[130:131], v[10:11], v[130:131] op_sel_hi:[0,1]
	v_mul_f32_e32 v10, v179, v179
	v_pk_add_f32 v[130:131], v[10:11], v[130:131] op_sel_hi:[0,1]
	v_mul_f32_e32 v10, v173, v173
	v_pk_add_f32 v[130:131], v[10:11], v[130:131] op_sel_hi:[0,1]
	v_mul_f32_e32 v10, v157, v157
	v_pk_add_f32 v[130:131], v[10:11], v[130:131] op_sel_hi:[0,1]
	v_mul_f32_e32 v10, v165, v165
	v_pk_add_f32 v[130:131], v[10:11], v[130:131] op_sel_hi:[0,1]
	v_pk_fma_f32 v[130:131], v[208:209], v[208:209], v[130:131]
	s_waitcnt vmcnt(0)
	v_mov_b32_e32 v209, v122
	v_mov_b32_e32 v10, v130
	s_nop 1
	v_permlane32_swap_b32_e32 v130, v10
	v_add_f32_e32 v10, v130, v10
	v_fmamk_f32 v10, v10, 0x3c000000, v215
	v_mul_f32_e32 v12, 0x4f800000, v10
	v_cmp_gt_f32_e32 vcc, s33, v10
	v_mov_b32_e32 v131, v26
	v_mov_b32_e32 v122, v127
	v_cndmask_b32_e32 v10, v10, v12, vcc
	v_sqrt_f32_e32 v12, v10
	v_mov_b32_e32 v134, v128
	v_mov_b32_e32 v135, v124
	v_mov_b32_e32 v124, v129
	v_add_u32_e32 v14, -1, v12
	v_fma_f32 v16, -v14, v12, v10
	v_cmp_ge_f32_e64 s[0:1], 0, v16
	v_add_u32_e32 v16, 1, v12
	v_mov_b32_e32 v128, v118
	v_cndmask_b32_e64 v14, v12, v14, s[0:1]
	v_fma_f32 v12, -v16, v12, v10
	v_cmp_lt_f32_e64 s[0:1], 0, v12
	v_mov_b32_e32 v239, v118
	v_mov_b32_e32 v118, v115
	v_cndmask_b32_e64 v12, v14, v16, s[0:1]
	v_mul_f32_e32 v14, 0x37800000, v12
	v_cndmask_b32_e32 v12, v12, v14, vcc
	v_cmp_class_f32_e32 vcc, v10, v216
	v_mov_b32_e32 v208, v126
	v_mov_b32_e32 v126, v120
	v_cndmask_b32_e32 v10, v12, v10, vcc
	v_div_scale_f32 v12, s[0:1], v10, v10, 1.0
	v_rcp_f32_e32 v14, v12
	v_mov_b32_e32 v129, v114
	v_mov_b32_e32 v238, v114
	v_mov_b32_e32 v114, v119
	v_fma_f32 v16, -v12, v14, 1.0
	v_fmac_f32_e32 v14, v16, v14
	v_div_scale_f32 v16, vcc, 1.0, v10, 1.0
	v_mul_f32_e32 v26, v16, v14
	v_fma_f32 v28, -v12, v26, v16
	v_fmac_f32_e32 v26, v28, v14
	v_fma_f32 v12, -v12, v26, v16
	v_div_fmas_f32 v12, v12, v14, v26
	v_div_fixup_f32 v10, v12, v10, 1.0
	v_pk_mul_f32 v[236:237], v[10:11], v[236:237] op_sel_hi:[0,1]
	v_pk_mul_f32 v[122:123], v[122:123], v[236:237]
	v_pk_mul_f32 v[234:235], v[10:11], v[234:235] op_sel_hi:[0,1]
	v_pk_mul_f32 v[124:125], v[124:125], v[234:235]
	v_pk_mul_f32 v[234:235], v[118:119], v[122:123]
	v_mov_b32_e32 v119, v120
	v_mov_b32_e32 v120, v117
	v_mov_b32_e32 v127, v116
	v_mov_b32_e32 v118, v116
	v_mov_b32_e32 v116, v121
	v_pk_mul_f32 v[120:121], v[120:121], v[124:125]
	v_pk_mul_f32 v[116:117], v[116:117], v[124:125]
	v_mov_b32_e32 v124, v110
	v_mov_b32_e32 v125, v106
	v_sub_f32_e32 v32, v120, v121
	v_pk_mul_f32 v[120:121], v[10:11], v[202:203] op_sel_hi:[0,1]
	v_pk_mul_f32 v[114:115], v[114:115], v[122:123]
	v_mov_b32_e32 v122, v112
	v_mov_b32_e32 v123, v108
	v_mov_b32_e32 v108, v113
	v_mov_b32_e32 v112, v102
	v_mov_b32_e32 v113, v98
	v_pk_mul_f32 v[120:121], v[124:125], v[120:121]
	v_pk_mul_f32 v[136:137], v[10:11], v[136:137] op_sel_hi:[0,1]
	v_pk_mul_f32 v[132:133], v[10:11], v[132:133] op_sel_hi:[0,1]
	v_pk_mul_f32 v[112:113], v[112:113], v[120:121]
	v_mov_b32_e32 v106, v111
	v_pk_mul_f32 v[110:111], v[10:11], v[210:211] op_sel_hi:[0,1]
	v_pk_mul_f32 v[136:137], v[208:209], v[136:137]
	v_mov_b32_e32 v209, v38
	v_pk_mul_f32 v[132:133], v[134:135], v[132:133]
	v_add_f32_e32 v38, v112, v113
	v_pk_mul_f32 v[112:113], v[10:11], v[142:143] op_sel_hi:[0,1]
	v_pk_mul_f32 v[106:107], v[106:107], v[110:111]
	v_pk_mul_f32 v[110:111], v[10:11], v[204:205] op_sel_hi:[0,1]
	v_mov_b32_e32 v210, v100
	v_mov_b32_e32 v211, v104
	v_mov_b32_e32 v236, v104
	v_mov_b32_e32 v237, v100
	v_pk_mul_f32 v[128:129], v[128:129], v[136:137]
	v_pk_mul_f32 v[126:127], v[126:127], v[132:133]
	v_pk_mul_f32 v[112:113], v[122:123], v[112:113]
	v_mov_b32_e32 v130, v30
	v_pk_mul_f32 v[108:109], v[108:109], v[110:111]
	v_mov_b32_e32 v104, v101
	v_add_f32_e32 v14, v128, v129
	v_pk_mul_f32 v[118:119], v[118:119], v[132:133]
	v_add_f32_e32 v30, v126, v127
	v_pk_mul_f32 v[126:127], v[210:211], v[112:113]
	v_pk_mul_f32 v[112:113], v[236:237], v[112:113]
	v_mov_b32_e32 v100, v105
	v_pk_mul_f32 v[104:105], v[104:105], v[108:109]
	v_sub_f32_e32 v28, v118, v119
	v_mov_b32_e32 v118, v76
	v_mul_f32_e32 v76, 0x3e0293ee, v14
	v_add_f32_e32 v14, v112, v113
	v_pk_mul_f32 v[108:109], v[100:101], v[108:109]
	v_mov_b32_e32 v122, v90
	v_mov_b32_e32 v123, v94
	v_mul_f32_e32 v112, 0x3e0293ee, v14
	v_sub_f32_e32 v14, v104, v105
	v_pk_mul_f32 v[104:105], v[10:11], v[200:201] op_sel_hi:[0,1]
;     ...
;       for (int dd = 0; dd < 2; ++dd) { const int d0 = hf * 4 + dd, f0 = dd * 16 + hi * 8;
;         const f32x8 cs = *(const f32x8*)(rcos + trow * 32 + f0), sn = *(const f32x8*)(rsin + trow * 32 + f0);
;         const f32x8 g1 = *(const f32x8*)(qgain + d0 * 16 + hi * 8), g2 = *(const f32x8*)(qgain + (d0 + 2) * 16 + hi * 8);
; #pragma unroll
;         for (int i = 0; i < 8; ++i) { const float y1 = x[d0][i] * rstd * g1[i], y2 = x[d0 + 2][i] * rstd * g2[i];
;           x[d0][i] = (y1 * cs[i] - y2 * sn[i]) * qsc; x[d0 + 2][i] = (y1 * sn[i] + y2 * cs[i]) * qsc; } } }
	v_mul_f32_e32 v113, 0x3e0293ee, v14
	v_add_f32_e32 v14, v108, v109
	v_pk_mul_f32 v[104:105], v[122:123], v[104:105]
	v_mov_b32_e32 v108, v82
	v_mov_b32_e32 v109, v86
	v_mov_b32_e32 v142, v86
	v_mov_b32_e32 v143, v82
	v_pk_mul_f32 v[108:109], v[108:109], v[104:105]
	v_sub_f32_e32 v16, v234, v235
	v_mul_f32_e32 v234, 0x3e0293ee, v14
	v_sub_f32_e32 v14, v108, v109
	v_pk_mul_f32 v[104:105], v[142:143], v[104:105]
	v_mul_f32_e32 v108, 0x3e0293ee, v14
	v_add_f32_e32 v14, v104, v105
	v_pk_mul_f32 v[104:105], v[10:11], v[138:139] op_sel_hi:[0,1]
	v_mov_b32_e32 v94, v91
	v_pk_mul_f32 v[90:91], v[94:95], v[104:105]
	v_mov_b32_e32 v86, v83
	v_mov_b32_e32 v110, v98
	v_mov_b32_e32 v111, v102
	v_pk_mul_f32 v[94:95], v[86:87], v[90:91]
	v_mov_b32_e32 v82, v87
	v_pk_mul_f32 v[110:111], v[110:111], v[120:121]
	v_mul_f32_e32 v109, 0x3e0293ee, v14
	v_sub_f32_e32 v14, v94, v95
	v_pk_mul_f32 v[82:83], v[82:83], v[90:91]
	v_mov_b32_e32 v102, v99
	v_mov_b32_e32 v98, v103
	v_mov_b32_e32 v100, v36
	v_sub_f32_e32 v36, v110, v111
	v_mov_b32_e32 v110, v92
	v_mov_b32_e32 v111, v96
	v_mul_f32_e32 v94, 0x3e0293ee, v14
	v_add_f32_e32 v14, v82, v83
	v_pk_mul_f32 v[82:83], v[10:11], v[144:145] op_sel_hi:[0,1]
	v_pk_mul_f32 v[204:205], v[102:103], v[106:107]
	v_pk_mul_f32 v[106:107], v[98:99], v[106:107]
	v_pk_mul_f32 v[82:83], v[110:111], v[82:83]
	v_mov_b32_e32 v86, v84
	v_mov_b32_e32 v87, v88
	v_add_f32_e32 v26, v114, v115
	v_mov_b32_e32 v114, v50
	v_add_f32_e32 v50, v106, v107
	v_mov_b32_e32 v106, v88
	v_mov_b32_e32 v107, v84
	v_pk_mul_f32 v[86:87], v[86:87], v[82:83]
	v_mul_f32_e32 v90, 0x3e0293ee, v14
	v_sub_f32_e32 v14, v86, v87
	v_pk_mul_f32 v[82:83], v[106:107], v[82:83]
	v_mul_f32_e32 v91, 0x3e0293ee, v14
	v_add_f32_e32 v14, v82, v83
	v_pk_mul_f32 v[82:83], v[10:11], v[198:199] op_sel_hi:[0,1]
	v_mov_b32_e32 v96, v93
	v_pk_mul_f32 v[82:83], v[96:97], v[82:83]
	v_mov_b32_e32 v88, v85
	v_pk_mul_f32 v[86:87], v[88:89], v[82:83]
	v_mov_b32_e32 v84, v89
	v_mul_f32_e32 v95, 0x3e0293ee, v14
	v_sub_f32_e32 v14, v86, v87
	v_pk_mul_f32 v[82:83], v[84:85], v[82:83]
	v_mov_b32_e32 v124, v74
	v_mov_b32_e32 v125, v78
	v_mul_f32_e32 v86, 0x3e0293ee, v14
	v_add_f32_e32 v14, v82, v83
	v_pk_mul_f32 v[82:83], v[10:11], v[196:197] op_sel_hi:[0,1]
	v_pk_mul_f32 v[82:83], v[124:125], v[82:83]
	v_mov_b32_e32 v84, v66
	v_mov_b32_e32 v85, v70
	v_mov_b32_e32 v120, v70
	v_mov_b32_e32 v121, v66
	v_pk_mul_f32 v[84:85], v[84:85], v[82:83]
	v_mul_f32_e32 v87, 0x3e0293ee, v14
	v_sub_f32_e32 v14, v84, v85
	v_pk_mul_f32 v[82:83], v[120:121], v[82:83]
	v_mul_f32_e32 v84, 0x3e0293ee, v14
	v_add_f32_e32 v14, v82, v83
	v_pk_mul_f32 v[82:83], v[10:11], v[140:141] op_sel_hi:[0,1]
	v_mov_b32_e32 v78, v75
	v_pk_mul_f32 v[74:75], v[78:79], v[82:83]
	v_mov_b32_e32 v70, v67
	v_pk_mul_f32 v[78:79], v[70:71], v[74:75]
	v_mov_b32_e32 v66, v71
	v_mul_f32_e32 v85, 0x3e0293ee, v14
	v_sub_f32_e32 v14, v78, v79
	v_pk_mul_f32 v[66:67], v[66:67], v[74:75]
	v_mov_b32_e32 v119, v80
	v_mul_f32_e32 v78, 0x3e0293ee, v14
	v_add_f32_e32 v14, v66, v67
	v_pk_mul_f32 v[66:67], v[10:11], v[150:151] op_sel_hi:[0,1]
	v_pk_mul_f32 v[66:67], v[118:119], v[66:67]
	v_mov_b32_e32 v70, v68
	v_mov_b32_e32 v71, v72
	v_mov_b32_e32 v208, v34
	v_add_f32_e32 v34, v116, v117
	v_mov_b32_e32 v116, v72
	v_mov_b32_e32 v117, v68
	v_pk_mul_f32 v[70:71], v[70:71], v[66:67]
	v_mul_f32_e32 v74, 0x3e0293ee, v14
	v_sub_f32_e32 v14, v70, v71
	v_pk_mul_f32 v[66:67], v[116:117], v[66:67]
	v_mul_f32_e32 v75, 0x3e0293ee, v14
	v_add_f32_e32 v14, v66, v67
	v_pk_mul_f32 v[66:67], v[10:11], v[194:195] op_sel_hi:[0,1]
	v_mov_b32_e32 v80, v77
	v_pk_mul_f32 v[66:67], v[80:81], v[66:67]
	v_mov_b32_e32 v72, v69
	v_pk_mul_f32 v[70:71], v[72:73], v[66:67]
	v_mov_b32_e32 v68, v73
	v_mul_f32_e32 v79, 0x3e0293ee, v14
	v_sub_f32_e32 v14, v70, v71
	v_pk_mul_f32 v[66:67], v[68:69], v[66:67]
	v_mov_b32_e32 v115, v54
	v_mul_f32_e32 v70, 0x3e0293ee, v14
	v_add_f32_e32 v14, v66, v67
	v_pk_mul_f32 v[66:67], v[10:11], v[192:193] op_sel_hi:[0,1]
	v_pk_mul_f32 v[66:67], v[66:67], v[114:115]
	v_mov_b32_e32 v68, v58
	v_mov_b32_e32 v69, v62
	v_mov_b32_e32 v132, v62
	v_mov_b32_e32 v133, v58
	v_pk_mul_f32 v[68:69], v[68:69], v[66:67]
	v_mul_f32_e32 v71, 0x3e0293ee, v14
	v_sub_f32_e32 v14, v68, v69
	v_pk_mul_f32 v[66:67], v[132:133], v[66:67]
	v_mul_f32_e32 v68, 0x3e0293ee, v14
	v_add_f32_e32 v14, v66, v67
	v_pk_mul_f32 v[66:67], v[10:11], v[146:147] op_sel_hi:[0,1]
	v_mov_b32_e32 v54, v51
	v_mul_f32_e32 v210, 0x3e0293ee, v50
	v_pk_mul_f32 v[50:51], v[66:67], v[54:55]
	v_mov_b32_e32 v62, v59
	v_pk_mul_f32 v[54:55], v[62:63], v[50:51]
	v_mov_b32_e32 v58, v63
	v_mul_f32_e32 v69, 0x3e0293ee, v14
	v_sub_f32_e32 v14, v54, v55
	v_pk_mul_f32 v[50:51], v[58:59], v[50:51]
	v_mov_b32_e32 v128, v52
	v_mov_b32_e32 v129, v56
	v_mul_f32_e32 v62, 0x3e0293ee, v14
	v_add_f32_e32 v14, v50, v51
	v_pk_mul_f32 v[50:51], v[10:11], v[152:153] op_sel_hi:[0,1]
	v_pk_mul_f32 v[50:51], v[50:51], v[128:129]
	v_mov_b32_e32 v54, v60
	v_mov_b32_e32 v55, v64
	v_mov_b32_e32 v134, v64
	v_mov_b32_e32 v135, v60
	v_pk_mul_f32 v[54:55], v[54:55], v[50:51]
	v_mul_f32_e32 v58, 0x3e0293ee, v14
	v_sub_f32_e32 v14, v54, v55
	v_pk_mul_f32 v[50:51], v[134:135], v[50:51]
	v_mul_f32_e32 v54, 0x3e0293ee, v14
	v_add_f32_e32 v14, v50, v51
	v_pk_mul_f32 v[50:51], v[10:11], v[190:191] op_sel_hi:[0,1]
	v_mov_b32_e32 v56, v53
	v_sub_f32_e32 v52, v126, v127
	v_pk_mul_f32 v[50:51], v[50:51], v[56:57]
	v_mov_b32_e32 v64, v61
	v_mul_f32_e32 v211, 0x3e0293ee, v52
	v_pk_mul_f32 v[52:53], v[64:65], v[50:51]
	v_mov_b32_e32 v60, v65
	v_mul_f32_e32 v55, 0x3e0293ee, v14
	v_sub_f32_e32 v14, v52, v53
	v_pk_mul_f32 v[50:51], v[60:61], v[50:51]
; #define PP_BAR(VM) do { if (VM) { asm volatile("s_waitcnt vmcnt(4) lgkmcnt(0)\n\ts_barrier" ::: "memory"); } else { asm volatile("s_waitcnt vmcnt(0) lgkmcnt(0)\n\ts_barrier" ::: "memory"); } } while (0)
; #define PP_BAR_PLAIN() asm volatile("s_waitcnt lgkmcnt(0)\n\ts_barrier" ::: "memory")
;     ...
; #pragma unroll
;         for (int i = 0; i < 8; ++i) { const float y1 = x[d0][i] * rstd * g1[i], y2 = x[d0 + 2][i] * rstd * g2[i];
;           x[d0][i] = (y1 * cs[i] - y2 * sn[i]) * qsc; x[d0 + 2][i] = (y1 * sn[i] + y2 * cs[i]) * qsc; } } }
; #pragma unroll
;     for (int d0 = 0; d0 < 8; ++d0) { u32x4 w = {cvtpk(x[d0][0], x[d0][1]), cvtpk(x[d0][2], x[d0][3]), cvtpk(x[d0][4], x[d0][5]), cvtpk(x[d0][6], x[d0][7])}; qr[d0] = *reinterpret_cast<bf16x8*>(&w); }
;     ...
;     const bool grpB = wid >= 4;
;     ...
;     m_reg = 0.f; f32x16 negm = f32x16{};
;     ...
;     if (grpB) PP_BAR_PLAIN();
;     qkt(pA0, pA1, KBUF(0), qr, r32, hi);
;     if (grpB) PP_BAR(2 < NT); else PP_BAR_PLAIN();
	v_mul_f32_e32 v56, 0x3e0293ee, v14
	v_add_f32_e32 v14, v50, v51
	v_pk_mul_f32 v[50:51], v[10:11], v[188:189] op_sel_hi:[0,1]
	v_pk_mul_f32 v[50:51], v[50:51], v[208:209]
	v_mov_b32_e32 v52, v42
	v_mov_b32_e32 v53, v46
	v_pk_mul_f32 v[238:239], v[238:239], v[136:137]
	v_mov_b32_e32 v136, v46
	v_mov_b32_e32 v137, v42
	v_pk_mul_f32 v[52:53], v[52:53], v[50:51]
	v_mul_f32_e32 v57, 0x3e0293ee, v14
	v_sub_f32_e32 v14, v52, v53
	v_pk_mul_f32 v[50:51], v[136:137], v[50:51]
	v_mov_b32_e32 v101, v40
	v_sub_f32_e32 v40, v204, v205
	v_mul_f32_e32 v204, 0x3e0293ee, v38
	v_mul_f32_e32 v52, 0x3e0293ee, v14
	v_add_f32_e32 v14, v50, v51
	v_pk_mul_f32 v[50:51], v[10:11], v[148:149] op_sel_hi:[0,1]
	v_mov_b32_e32 v38, v35
	v_mul_f32_e32 v202, 0x3e0293ee, v34
	v_pk_mul_f32 v[34:35], v[50:51], v[38:39]
	v_mov_b32_e32 v46, v43
	v_pk_mul_f32 v[38:39], v[46:47], v[34:35]
	v_mov_b32_e32 v42, v47
	v_mul_f32_e32 v53, 0x3e0293ee, v14
	v_sub_f32_e32 v14, v38, v39
	v_pk_mul_f32 v[34:35], v[42:43], v[34:35]
	v_mul_f32_e32 v46, 0x3e0293ee, v14
	v_add_f32_e32 v14, v34, v35
	v_pk_mul_f32 v[34:35], v[10:11], v[158:159] op_sel_hi:[0,1]
	v_pk_mul_f32 v[34:35], v[34:35], v[100:101]
	v_mov_b32_e32 v38, v44
	v_mov_b32_e32 v39, v48
	v_mov_b32_e32 v98, v48
	v_mov_b32_e32 v99, v44
	v_pk_mul_f32 v[38:39], v[38:39], v[34:35]
	v_mul_f32_e32 v42, 0x3e0293ee, v14
	v_sub_f32_e32 v14, v38, v39
	v_pk_mul_f32 v[34:35], v[98:99], v[34:35]
	v_mul_f32_e32 v205, 0x3e0293ee, v40
	v_mul_f32_e32 v38, 0x3e0293ee, v14
	v_add_f32_e32 v14, v34, v35
	v_pk_mul_f32 v[34:35], v[10:11], v[186:187] op_sel_hi:[0,1]
	v_mov_b32_e32 v40, v37
	v_pk_mul_f32 v[34:35], v[34:35], v[40:41]
	v_mov_b32_e32 v48, v45
	v_mul_f32_e32 v203, 0x3e0293ee, v36
	v_pk_mul_f32 v[36:37], v[48:49], v[34:35]
	v_mov_b32_e32 v44, v49
	v_mul_f32_e32 v39, 0x3e0293ee, v14
	v_sub_f32_e32 v14, v36, v37
	v_pk_mul_f32 v[34:35], v[44:45], v[34:35]
	v_mul_f32_e32 v40, 0x3e0293ee, v14
	v_add_f32_e32 v14, v34, v35
	v_pk_mul_f32 v[34:35], v[10:11], v[184:185] op_sel_hi:[0,1]
	v_pk_mul_f32 v[34:35], v[34:35], v[130:131]
	v_mov_b32_e32 v36, v18
	v_mov_b32_e32 v37, v22
	v_mov_b32_e32 v102, v22
	v_mov_b32_e32 v103, v18
	v_pk_mul_f32 v[36:37], v[36:37], v[34:35]
	v_mul_f32_e32 v41, 0x3e0293ee, v14
	v_sub_f32_e32 v14, v36, v37
	v_pk_mul_f32 v[34:35], v[102:103], v[34:35]
	v_mul_f32_e32 v126, 0x3e0293ee, v26
	v_mul_f32_e32 v36, 0x3e0293ee, v14
	v_add_f32_e32 v14, v34, v35
	v_pk_mul_f32 v[34:35], v[10:11], v[154:155] op_sel_hi:[0,1]
	v_mov_b32_e32 v26, v31
	v_pk_mul_f32 v[26:27], v[34:35], v[26:27]
	v_mov_b32_e32 v22, v19
	v_mul_f32_e32 v163, 0x3e0293ee, v30
	v_pk_mul_f32 v[30:31], v[22:23], v[26:27]
	v_mov_b32_e32 v18, v23
	v_mul_f32_e32 v37, 0x3e0293ee, v14
	v_sub_f32_e32 v14, v30, v31
	v_pk_mul_f32 v[18:19], v[18:19], v[26:27]
	v_mul_f32_e32 v30, 0x3e0293ee, v14
	v_add_f32_e32 v14, v18, v19
	v_pk_mul_f32 v[18:19], v[10:11], v[160:161] op_sel_hi:[0,1]
	v_pk_mul_f32 v[18:19], v[18:19], v[182:183]
	v_mov_b32_e32 v22, v20
	v_mov_b32_e32 v23, v24
	v_pk_mul_f32 v[22:23], v[22:23], v[18:19]
	v_mul_f32_e32 v26, 0x3e0293ee, v14
	v_sub_f32_e32 v14, v22, v23
	v_pk_mul_f32 v[18:19], v[180:181], v[18:19]
	v_mul_f32_e32 v127, 0x3e0293ee, v28
	v_mul_f32_e32 v27, 0x3e0293ee, v14
	v_add_f32_e32 v14, v18, v19
	v_pk_mul_f32 v[18:19], v[10:11], v[178:179] op_sel_hi:[0,1]
	v_mov_b32_e32 v28, v33
	v_pk_mul_f32 v[18:19], v[18:19], v[28:29]
	v_mov_b32_e32 v24, v21
	v_pk_mul_f32 v[22:23], v[24:25], v[18:19]
	v_mov_b32_e32 v20, v25
	v_mul_f32_e32 v31, 0x3e0293ee, v14
	v_sub_f32_e32 v14, v22, v23
	v_pk_mul_f32 v[18:19], v[20:21], v[18:19]
	v_mul_f32_e32 v22, 0x3e0293ee, v14
	v_add_f32_e32 v14, v18, v19
	v_pk_mul_f32 v[18:19], v[10:11], v[172:173] op_sel_hi:[0,1]
	v_pk_mul_f32 v[18:19], v[18:19], v[176:177]
	v_mov_b32_e32 v20, v2
	v_mov_b32_e32 v21, v6
	v_mov_b32_e32 v174, v6
	v_mov_b32_e32 v175, v2
	v_pk_mul_f32 v[20:21], v[20:21], v[18:19]
	v_pk_mul_f32 v[18:19], v[174:175], v[18:19]
	v_sub_f32_e32 v2, v20, v21
	v_mul_f32_e32 v23, 0x3e0293ee, v14
	v_mul_f32_e32 v20, 0x3e0293ee, v2
	v_add_f32_e32 v2, v18, v19
	v_pk_mul_f32 v[18:19], v[10:11], v[156:157] op_sel_hi:[0,1]
	v_mov_b32_e32 v14, v11
	v_pk_mul_f32 v[14:15], v[18:19], v[14:15]
	v_mov_b32_e32 v6, v3
	v_pk_mul_f32 v[18:19], v[6:7], v[14:15]
	v_mul_f32_e32 v21, 0x3e0293ee, v2
	v_sub_f32_e32 v2, v18, v19
	v_mul_f32_e32 v11, 0x3e0293ee, v2
	v_mov_b32_e32 v2, v7
	v_pk_mul_f32 v[2:3], v[2:3], v[14:15]
	v_mov_b32_e32 v168, v8
	v_add_f32_e32 v2, v2, v3
	v_mul_f32_e32 v14, 0x3e0293ee, v2
	v_pk_mul_f32 v[2:3], v[10:11], v[164:165] op_sel_hi:[0,1]
	v_mov_b32_e32 v169, v4
	v_pk_mul_f32 v[2:3], v[2:3], v[170:171]
	v_mov_b32_e32 v6, v4
	v_mov_b32_e32 v7, v8
	v_pk_mul_f32 v[6:7], v[6:7], v[2:3]
	v_pk_mul_f32 v[2:3], v[168:169], v[2:3]
	v_mul_f32_e32 v92, 0x3e0293ee, v16
	v_add_f32_e32 v2, v2, v3
	v_mul_f32_e32 v18, 0x3e0293ee, v2
	v_pk_mul_f32 v[2:3], v[10:11], v[166:167] op_sel_hi:[0,1]
	v_mov_b32_e32 v16, v13
	v_pk_mul_f32 v[2:3], v[2:3], v[16:17]
	v_mov_b32_e32 v8, v5
	v_sub_f32_e32 v4, v6, v7
	v_pk_mul_f32 v[6:7], v[8:9], v[2:3]
	v_mul_f32_e32 v15, 0x3e0293ee, v4
	v_sub_f32_e32 v4, v6, v7
	s_cmp_gt_i32 s10, 3
	v_mul_f32_e32 v6, 0x3e0293ee, v4
	v_mov_b32_e32 v4, v9
	s_cselect_b64 s[82:83], -1, 0
	s_cmp_lt_i32 s10, 4
	v_pk_mul_f32 v[2:3], v[4:5], v[2:3]
	s_cselect_b64 s[0:1], -1, 0
	v_sub_f32_e32 v12, v238, v239
	v_add_f32_e32 v2, v2, v3
	s_and_b64 vcc, exec, s[0:1]
	v_mul_f32_e32 v12, 0x3e0293ee, v12
	v_mul_f32_e32 v32, 0x3e0293ee, v32
	v_mul_f32_e32 v2, 0x3e0293ee, v2
	v_cvt_pk_bf16_f32 v158, v12, v92
	v_cvt_pk_bf16_f32 v159, v127, v32
	v_cvt_pk_bf16_f32 v160, v203, v205
	v_cvt_pk_bf16_f32 v161, v211, v113
	v_cvt_pk_bf16_f32 v154, v108, v94
	v_cvt_pk_bf16_f32 v155, v91, v86
	v_cvt_pk_bf16_f32 v156, v84, v78
	v_cvt_pk_bf16_f32 v157, v75, v70
	v_cvt_pk_bf16_f32 v150, v76, v126
	v_cvt_pk_bf16_f32 v151, v163, v202
	v_cvt_pk_bf16_f32 v152, v204, v210
	v_cvt_pk_bf16_f32 v153, v112, v234
	v_cvt_pk_bf16_f32 v146, v109, v90
	v_cvt_pk_bf16_f32 v147, v95, v87
	v_cvt_pk_bf16_f32 v148, v85, v74
	v_cvt_pk_bf16_f32 v149, v79, v71
	v_cvt_pk_bf16_f32 v142, v68, v62
	v_cvt_pk_bf16_f32 v143, v54, v56
	v_cvt_pk_bf16_f32 v144, v52, v46
	v_cvt_pk_bf16_f32 v145, v38, v40
	v_cvt_pk_bf16_f32 v138, v36, v30
	v_cvt_pk_bf16_f32 v139, v27, v22
	v_cvt_pk_bf16_f32 v140, v20, v11
	v_cvt_pk_bf16_f32 v141, v15, v6
	v_cvt_pk_bf16_f32 v134, v69, v58
	v_cvt_pk_bf16_f32 v135, v55, v57
	v_cvt_pk_bf16_f32 v136, v53, v42
	v_cvt_pk_bf16_f32 v137, v39, v41
	v_cvt_pk_bf16_f32 v130, v37, v26
	v_cvt_pk_bf16_f32 v131, v31, v23
	v_cvt_pk_bf16_f32 v132, v21, v14
	v_cvt_pk_bf16_f32 v133, v18, v2
	s_cbranch_vccnz .LBB0_51
	s_waitcnt lgkmcnt(0)
	s_barrier
